# v12 + fp8 K-loops: open barrier before the first MFMA, satisfied inner lgkmcnt waits removed
# speedup vs baseline: 1.0033x; 1.0033x over previous
.LBB0_1420:
	ds_read_b128 v[146:149], v138
	ds_read_b128 v[150:153], v138 offset:1024
	ds_read_b128 v[154:157], v138 offset:2048
	ds_read_b128 v[158:161], v138 offset:3072
	ds_read_b128 v[162:165], v139
	ds_read_b128 v[166:169], v139 offset:1024
	ds_read_b128 v[170:173], v139 offset:2048
	ds_read_b128 v[174:177], v139 offset:3072
	s_add_i32 s14, s73, 0xfff40080
	s_cmp_eq_u32 s60, s75
	s_cselect_b32 s76, s71, s14
	s_cselect_b32 s78, s72, s74
	s_or_b32 s77, s76, 0x80
	s_add_i32 s14, s73, 0xfffc0000
	s_mov_b32 m0, s61
	ds_read_b128 v[178:181], v140
	ds_read_b128 v[182:185], v140 offset:1024
	ds_read_b128 v[186:189], v140 offset:2048
	ds_read_b128 v[190:193], v140 offset:3072
	ds_read_b128 v[194:197], v140 offset:4096
	ds_read_b128 v[198:201], v140 offset:5120
	ds_read_b128 v[202:205], v140 offset:6144
	ds_read_b128 v[206:209], v140 offset:7168
	buffer_load_dwordx4 v136, s[16:19], s14 offen lds
	s_mov_b32 m0, s62
	s_nop 0
	buffer_load_dwordx4 v136, s[16:19], s73 offen lds
	s_waitcnt vmcnt(8)
	s_waitcnt lgkmcnt(0)
	s_setprio 1
	s_barrier
	v_mfma_f32_16x16x128_f8f6f4 v[118:121], v[146:153], v[178:185], v[118:121]
	v_mfma_f32_16x16x128_f8f6f4 v[114:117], v[154:161], v[178:185], v[114:117]
	v_mfma_f32_16x16x128_f8f6f4 v[110:113], v[146:153], v[186:193], v[110:113]
	v_mfma_f32_16x16x128_f8f6f4 v[102:105], v[154:161], v[186:193], v[102:105]
	v_mfma_f32_16x16x128_f8f6f4 v[126:129], v[162:169], v[178:185], v[126:129]
	v_mfma_f32_16x16x128_f8f6f4 v[122:125], v[170:177], v[178:185], v[122:125]
	v_mfma_f32_16x16x128_f8f6f4 v[106:109], v[162:169], v[186:193], v[106:109]
	v_mfma_f32_16x16x128_f8f6f4 v[98:101], v[170:177], v[186:193], v[98:101]
	v_mfma_f32_16x16x128_f8f6f4 v[210:213], v[146:153], v[194:201], v[94:97]
	v_mfma_f32_16x16x128_f8f6f4 v[214:217], v[154:161], v[194:201], v[86:89]
	v_mfma_f32_16x16x128_f8f6f4 v[218:221], v[146:153], v[202:209], v[78:81]
	v_mfma_f32_16x16x128_f8f6f4 v[222:225], v[154:161], v[202:209], v[70:73]
	v_mfma_f32_16x16x128_f8f6f4 v[178:181], v[162:169], v[194:201], v[90:93]
	v_mfma_f32_16x16x128_f8f6f4 v[182:185], v[170:177], v[194:201], v[82:85]
	v_mfma_f32_16x16x128_f8f6f4 v[186:189], v[162:169], v[202:209], v[74:77]
	v_mfma_f32_16x16x128_f8f6f4 v[190:193], v[170:177], v[202:209], v[66:69]
	s_setprio 0
	s_barrier
	s_mov_b32 m0, s31
	s_mov_b32 s14, s18
	s_mov_b32 s15, s19
	s_nop 1
	ds_read_b128 v[66:69], v140 offset:16384
	ds_read_b128 v[70:73], v140 offset:17408
	ds_read_b128 v[74:77], v140 offset:18432
	ds_read_b128 v[78:81], v140 offset:19456
	ds_read_b128 v[82:85], v140 offset:20480
	ds_read_b128 v[86:89], v140 offset:21504
	ds_read_b128 v[90:93], v140 offset:22528
	ds_read_b128 v[94:97], v140 offset:23552
	buffer_load_dwordx4 v137, s[12:15], s78 offen lds
	s_add_i32 s79, s78, 0x40000
	s_mov_b32 m0, s46
	s_nop 0
	buffer_load_dwordx4 v137, s[12:15], s79 offen lds
	s_add_i32 s79, s78, 0x80000
	s_mov_b32 m0, s47
	s_nop 0
	buffer_load_dwordx4 v137, s[12:15], s79 offen lds
	s_add_i32 s79, s78, 0xc0000
	s_mov_b32 m0, s48
	s_nop 0
	buffer_load_dwordx4 v137, s[12:15], s79 offen lds
	s_mov_b32 m0, s30
	s_add_i32 s79, s76, 0x40000
	buffer_load_dwordx4 v136, s[16:19], s76 offen lds
	s_mov_b32 m0, s49
	s_nop 0
	buffer_load_dwordx4 v136, s[16:19], s79 offen lds
	s_waitcnt vmcnt(8)
	s_waitcnt lgkmcnt(0)
	s_setprio 1
	s_barrier
	v_mfma_f32_16x16x128_f8f6f4 v[62:65], v[146:153], v[66:73], v[62:65]
	v_mfma_f32_16x16x128_f8f6f4 v[54:57], v[154:161], v[66:73], v[54:57]
	v_mfma_f32_16x16x128_f8f6f4 v[46:49], v[146:153], v[74:81], v[46:49]
	v_mfma_f32_16x16x128_f8f6f4 v[58:61], v[162:169], v[66:73], v[58:61]
	v_mfma_f32_16x16x128_f8f6f4 v[50:53], v[170:177], v[66:73], v[50:53]
	v_mfma_f32_16x16x128_f8f6f4 v[42:45], v[162:169], v[74:81], v[42:45]
	v_mfma_f32_16x16x128_f8f6f4 v[202:205], v[154:161], v[74:81], v[38:41]
	v_mfma_f32_16x16x128_f8f6f4 v[206:209], v[146:153], v[82:89], v[30:33]
	v_mfma_f32_16x16x128_f8f6f4 v[226:229], v[154:161], v[82:89], v[22:25]
	v_mfma_f32_16x16x128_f8f6f4 v[230:233], v[146:153], v[90:97], v[14:17]
	v_mfma_f32_16x16x128_f8f6f4 v[234:237], v[154:161], v[90:97], v[6:9]
	v_mfma_f32_16x16x128_f8f6f4 v[238:241], v[170:177], v[74:81], v[34:37]
	v_mfma_f32_16x16x128_f8f6f4 v[242:245], v[162:169], v[82:89], v[26:29]
	v_mfma_f32_16x16x128_f8f6f4 v[246:249], v[170:177], v[82:89], v[18:21]
	v_mfma_f32_16x16x128_f8f6f4 v[250:253], v[162:169], v[90:97], v[10:13]
	v_mfma_f32_16x16x128_f8f6f4 v[130:133], v[170:177], v[90:97], v[2:5]
	s_setprio 0
	s_barrier
	s_nop 4
	ds_read_b128 v[2:5], v141
	ds_read_b128 v[6:9], v141 offset:1024
	ds_read_b128 v[146:149], v141 offset:2048
	ds_read_b128 v[150:153], v141 offset:3072
	ds_read_b128 v[154:157], v142
	ds_read_b128 v[158:161], v142 offset:1024
	ds_read_b128 v[162:165], v142 offset:2048
	ds_read_b128 v[166:169], v142 offset:3072
	s_mov_b32 m0, s50
	s_add_i32 s79, s76, 0x80000
	ds_read_b128 v[10:13], v140 offset:32768
	ds_read_b128 v[14:17], v140 offset:33792
	ds_read_b128 v[18:21], v140 offset:34816
	ds_read_b128 v[22:25], v140 offset:35840
	ds_read_b128 v[26:29], v140 offset:36864
	ds_read_b128 v[30:33], v140 offset:37888
	ds_read_b128 v[34:37], v140 offset:38912
	ds_read_b128 v[38:41], v140 offset:39936
	buffer_load_dwordx4 v136, s[16:19], s79 offen lds
	s_add_i32 s79, s76, 0xc0000
	s_mov_b32 m0, s51
	s_nop 0
	buffer_load_dwordx4 v136, s[16:19], s79 offen lds
	s_waitcnt vmcnt(8)
	s_waitcnt lgkmcnt(0)
	s_setprio 1
	s_barrier
	v_mfma_f32_16x16x128_f8f6f4 v[118:121], v[2:9], v[10:17], v[118:121]
	v_mfma_f32_16x16x128_f8f6f4 v[114:117], v[146:153], v[10:17], v[114:117]
	v_mfma_f32_16x16x128_f8f6f4 v[110:113], v[2:9], v[18:25], v[110:113]
	v_mfma_f32_16x16x128_f8f6f4 v[102:105], v[146:153], v[18:25], v[102:105]
	v_mfma_f32_16x16x128_f8f6f4 v[94:97], v[2:9], v[26:33], v[210:213]
	v_mfma_f32_16x16x128_f8f6f4 v[86:89], v[146:153], v[26:33], v[214:217]
	v_mfma_f32_16x16x128_f8f6f4 v[78:81], v[2:9], v[34:41], v[218:221]
	v_mfma_f32_16x16x128_f8f6f4 v[70:73], v[146:153], v[34:41], v[222:225]
	v_mfma_f32_16x16x128_f8f6f4 v[126:129], v[154:161], v[10:17], v[126:129]
	v_mfma_f32_16x16x128_f8f6f4 v[122:125], v[162:169], v[10:17], v[122:125]
	v_mfma_f32_16x16x128_f8f6f4 v[106:109], v[154:161], v[18:25], v[106:109]
	v_mfma_f32_16x16x128_f8f6f4 v[98:101], v[162:169], v[18:25], v[98:101]
	v_mfma_f32_16x16x128_f8f6f4 v[90:93], v[154:161], v[26:33], v[178:181]
	v_mfma_f32_16x16x128_f8f6f4 v[82:85], v[162:169], v[26:33], v[182:185]
	v_mfma_f32_16x16x128_f8f6f4 v[74:77], v[154:161], v[34:41], v[186:189]
	v_mfma_f32_16x16x128_f8f6f4 v[66:69], v[162:169], v[34:41], v[190:193]
	s_setprio 0
	s_barrier
	s_mov_b32 m0, s54
	s_or_b32 s79, s78, 0x80
	ds_read_b128 v[170:173], v140 offset:49152
	ds_read_b128 v[174:177], v140 offset:50176
	ds_read_b128 v[178:181], v140 offset:51200
	ds_read_b128 v[182:185], v140 offset:52224
	ds_read_b128 v[186:189], v140 offset:53248
	ds_read_b128 v[190:193], v140 offset:54272
	ds_read_b128 v[194:197], v140 offset:55296
	ds_read_b128 v[198:201], v140 offset:56320
	buffer_load_dwordx4 v137, s[12:15], s79 offen lds
	s_add_i32 s79, s78, 0x40080
	s_mov_b32 m0, s55
	s_add_i32 s76, s76, 0x40080
	buffer_load_dwordx4 v137, s[12:15], s79 offen lds
	s_add_i32 s79, s78, 0x80080
	s_mov_b32 m0, s58
	s_add_i32 s78, s78, 0xc0080
	buffer_load_dwordx4 v137, s[12:15], s79 offen lds
	s_mov_b32 m0, s59
	s_nop 0
	buffer_load_dwordx4 v137, s[12:15], s78 offen lds
	s_mov_b32 m0, s56
	s_nop 0
	buffer_load_dwordx4 v136, s[16:19], s77 offen lds
	s_mov_b32 m0, s57
	s_nop 0
	buffer_load_dwordx4 v136, s[16:19], s76 offen lds
	s_waitcnt vmcnt(8)
	s_waitcnt lgkmcnt(0)
	s_setprio 1
	s_barrier
	v_mfma_f32_16x16x128_f8f6f4 v[62:65], v[2:9], v[170:177], v[62:65]
	v_mfma_f32_16x16x128_f8f6f4 v[54:57], v[146:153], v[170:177], v[54:57]
	v_mfma_f32_16x16x128_f8f6f4 v[46:49], v[2:9], v[178:185], v[46:49]
	v_mfma_f32_16x16x128_f8f6f4 v[38:41], v[146:153], v[178:185], v[202:205]
	v_mfma_f32_16x16x128_f8f6f4 v[30:33], v[2:9], v[186:193], v[206:209]
	v_mfma_f32_16x16x128_f8f6f4 v[22:25], v[146:153], v[186:193], v[226:229]
	v_mfma_f32_16x16x128_f8f6f4 v[14:17], v[2:9], v[194:201], v[230:233]
	v_mfma_f32_16x16x128_f8f6f4 v[6:9], v[146:153], v[194:201], v[234:237]
	v_mfma_f32_16x16x128_f8f6f4 v[58:61], v[154:161], v[170:177], v[58:61]
	v_mfma_f32_16x16x128_f8f6f4 v[50:53], v[162:169], v[170:177], v[50:53]
	v_mfma_f32_16x16x128_f8f6f4 v[42:45], v[154:161], v[178:185], v[42:45]
	v_mfma_f32_16x16x128_f8f6f4 v[34:37], v[162:169], v[178:185], v[238:241]
	v_mfma_f32_16x16x128_f8f6f4 v[26:29], v[154:161], v[186:193], v[242:245]
	v_mfma_f32_16x16x128_f8f6f4 v[18:21], v[162:169], v[186:193], v[246:249]
	v_mfma_f32_16x16x128_f8f6f4 v[10:13], v[154:161], v[194:201], v[250:253]
	v_mfma_f32_16x16x128_f8f6f4 v[2:5], v[162:169], v[194:201], v[130:133]
	s_setprio 0
	s_barrier
	s_add_i32 s75, s75, 2
	s_addk_i32 s73, 0x100
	s_addk_i32 s74, 0x100
	s_cmp_ge_i32 s75, s25
	s_cbranch_scc0 .LBB0_1420
	s_and_b64 vcc, exec, s[44:45]
	s_cbranch_vccz .LBB0_1423

.LBB0_1567:
	ds_read_b128 v[134:137], v225
	ds_read_b128 v[138:141], v225 offset:1024
	ds_read_b128 v[142:145], v225 offset:2048
	ds_read_b128 v[146:149], v225 offset:3072
	ds_read_b128 v[150:153], v226
	ds_read_b128 v[154:157], v226 offset:1024
	ds_read_b128 v[158:161], v226 offset:2048
	ds_read_b128 v[162:165], v226 offset:3072
	s_add_i32 s18, s8, 0xffdfc080
	s_cmp_eq_u32 s71, s55
	s_cselect_b32 s56, s6, s18
	s_cselect_b32 s91, s7, s9
	s_or_b32 s57, s56, 0x80
	s_add_i32 s18, s8, 0xfff54000
	s_mov_b32 m0, s72
	ds_read_b128 v[166:169], v227
	ds_read_b128 v[170:173], v227 offset:1024
	ds_read_b128 v[174:177], v227 offset:2048
	ds_read_b128 v[178:181], v227 offset:3072
	ds_read_b128 v[182:185], v227 offset:4096
	ds_read_b128 v[186:189], v227 offset:5120
	ds_read_b128 v[190:193], v227 offset:6144
	ds_read_b128 v[194:197], v227 offset:7168
	buffer_load_dwordx4 v223, s[12:15], s18 offen lds
	s_mov_b32 m0, s75
	s_nop 0
	buffer_load_dwordx4 v223, s[12:15], s8 offen lds
	s_waitcnt vmcnt(8)
	s_waitcnt lgkmcnt(0)
	s_setprio 1
	s_barrier
	v_mfma_f32_16x16x128_f8f6f4 v[126:129], v[134:141], v[166:173], v[126:129]
	v_mfma_f32_16x16x128_f8f6f4 v[122:125], v[142:149], v[166:173], v[122:125]
	v_mfma_f32_16x16x128_f8f6f4 v[118:121], v[134:141], v[174:181], v[118:121]
	v_mfma_f32_16x16x128_f8f6f4 v[114:117], v[142:149], v[174:181], v[114:117]
	v_mfma_f32_16x16x128_f8f6f4 v[106:109], v[134:141], v[182:189], v[106:109]
	v_mfma_f32_16x16x128_f8f6f4 v[98:101], v[142:149], v[182:189], v[98:101]
	v_mfma_f32_16x16x128_f8f6f4 v[110:113], v[150:157], v[166:173], v[110:113]
	v_mfma_f32_16x16x128_f8f6f4 v[102:105], v[158:165], v[166:173], v[102:105]
	v_mfma_f32_16x16x128_f8f6f4 v[198:201], v[134:141], v[190:197], v[90:93]
	v_mfma_f32_16x16x128_f8f6f4 v[202:205], v[142:149], v[190:197], v[82:85]
	v_mfma_f32_16x16x128_f8f6f4 v[166:169], v[150:157], v[174:181], v[94:97]
	v_mfma_f32_16x16x128_f8f6f4 v[170:173], v[158:165], v[174:181], v[86:89]
	v_mfma_f32_16x16x128_f8f6f4 v[174:177], v[150:157], v[182:189], v[78:81]
	v_mfma_f32_16x16x128_f8f6f4 v[178:181], v[158:165], v[182:189], v[74:77]
	v_mfma_f32_16x16x128_f8f6f4 v[182:185], v[150:157], v[190:197], v[70:73]
	v_mfma_f32_16x16x128_f8f6f4 v[186:189], v[158:165], v[190:197], v[66:69]
	s_setprio 0
	s_barrier
	s_mov_b32 m0, s27
	s_mov_b32 s18, s14
	s_mov_b32 s19, s15
	s_nop 1
	ds_read_b128 v[66:69], v227 offset:16384
	ds_read_b128 v[70:73], v227 offset:17408
	ds_read_b128 v[74:77], v227 offset:18432
	ds_read_b128 v[78:81], v227 offset:19456
	ds_read_b128 v[82:85], v227 offset:20480
	ds_read_b128 v[86:89], v227 offset:21504
	ds_read_b128 v[90:93], v227 offset:22528
	ds_read_b128 v[94:97], v227 offset:23552
	buffer_load_dwordx4 v224, s[16:19], s91 offen lds
	s_add_i32 s92, s91, 0xac000
	s_mov_b32 m0, s30
	s_nop 0
	buffer_load_dwordx4 v224, s[16:19], s92 offen lds
	s_add_i32 s92, s91, 0x158000
	s_mov_b32 m0, s31
	s_nop 0
	buffer_load_dwordx4 v224, s[16:19], s92 offen lds
	s_add_i32 s92, s91, 0x204000
	s_mov_b32 m0, s51
	s_nop 0
	buffer_load_dwordx4 v224, s[16:19], s92 offen lds
	s_mov_b32 m0, s25
	s_add_i32 s92, s56, 0xac000
	buffer_load_dwordx4 v223, s[12:15], s56 offen lds
	s_mov_b32 m0, s58
	s_nop 0
	buffer_load_dwordx4 v223, s[12:15], s92 offen lds
	s_waitcnt vmcnt(8)
	s_waitcnt lgkmcnt(0)
	s_setprio 1
	s_barrier
	v_mfma_f32_16x16x128_f8f6f4 v[62:65], v[134:141], v[66:73], v[62:65]
	v_mfma_f32_16x16x128_f8f6f4 v[58:61], v[142:149], v[66:73], v[58:61]
	v_mfma_f32_16x16x128_f8f6f4 v[54:57], v[134:141], v[74:81], v[54:57]
	v_mfma_f32_16x16x128_f8f6f4 v[50:53], v[142:149], v[74:81], v[50:53]
	v_mfma_f32_16x16x128_f8f6f4 v[190:193], v[134:141], v[82:89], v[42:45]
	v_mfma_f32_16x16x128_f8f6f4 v[194:197], v[142:149], v[82:89], v[34:37]
	v_mfma_f32_16x16x128_f8f6f4 v[206:209], v[134:141], v[90:97], v[26:29]
	v_mfma_f32_16x16x128_f8f6f4 v[210:213], v[142:149], v[90:97], v[18:21]
	v_mfma_f32_16x16x128_f8f6f4 v[214:217], v[150:157], v[66:73], v[46:49]
	v_mfma_f32_16x16x128_f8f6f4 v[218:221], v[158:165], v[66:73], v[38:41]
	v_mfma_f32_16x16x128_f8f6f4 v[234:237], v[150:157], v[74:81], v[30:33]
	v_mfma_f32_16x16x128_f8f6f4 v[238:241], v[158:165], v[74:81], v[22:25]
	v_mfma_f32_16x16x128_f8f6f4 v[242:245], v[150:157], v[82:89], v[14:17]
	v_mfma_f32_16x16x128_f8f6f4 v[246:249], v[158:165], v[82:89], v[10:13]
	v_mfma_f32_16x16x128_f8f6f4 v[250:253], v[150:157], v[90:97], v[6:9]
	v_mfma_f32_16x16x128_f8f6f4 v[130:133], v[158:165], v[90:97], v[2:5]
	s_setprio 0
	s_barrier
	s_nop 4
	ds_read_b128 v[2:5], v228
	ds_read_b128 v[6:9], v228 offset:1024
	ds_read_b128 v[10:13], v228 offset:2048
	ds_read_b128 v[14:17], v228 offset:3072
	ds_read_b128 v[134:137], v229
	ds_read_b128 v[138:141], v229 offset:1024
	ds_read_b128 v[142:145], v229 offset:2048
	ds_read_b128 v[146:149], v229 offset:3072
	s_mov_b32 m0, s59
	s_add_i32 s92, s56, 0x158000
	ds_read_b128 v[18:21], v227 offset:32768
	ds_read_b128 v[22:25], v227 offset:33792
	ds_read_b128 v[26:29], v227 offset:34816
	ds_read_b128 v[30:33], v227 offset:35840
	ds_read_b128 v[34:37], v227 offset:36864
	ds_read_b128 v[38:41], v227 offset:37888
	ds_read_b128 v[42:45], v227 offset:38912
	ds_read_b128 v[46:49], v227 offset:39936
	buffer_load_dwordx4 v223, s[12:15], s92 offen lds
	s_add_i32 s92, s56, 0x204000
	s_mov_b32 m0, s60
	s_nop 0
	buffer_load_dwordx4 v223, s[12:15], s92 offen lds
	s_waitcnt vmcnt(8)
	s_waitcnt lgkmcnt(0)
	s_setprio 1
	s_barrier
	v_mfma_f32_16x16x128_f8f6f4 v[126:129], v[2:9], v[18:25], v[126:129]
	v_mfma_f32_16x16x128_f8f6f4 v[122:125], v[10:17], v[18:25], v[122:125]
	v_mfma_f32_16x16x128_f8f6f4 v[118:121], v[2:9], v[26:33], v[118:121]
	v_mfma_f32_16x16x128_f8f6f4 v[114:117], v[10:17], v[26:33], v[114:117]
	v_mfma_f32_16x16x128_f8f6f4 v[106:109], v[2:9], v[34:41], v[106:109]
	v_mfma_f32_16x16x128_f8f6f4 v[98:101], v[10:17], v[34:41], v[98:101]
	v_mfma_f32_16x16x128_f8f6f4 v[90:93], v[2:9], v[42:49], v[198:201]
	v_mfma_f32_16x16x128_f8f6f4 v[82:85], v[10:17], v[42:49], v[202:205]
	v_mfma_f32_16x16x128_f8f6f4 v[110:113], v[134:141], v[18:25], v[110:113]
	v_mfma_f32_16x16x128_f8f6f4 v[102:105], v[142:149], v[18:25], v[102:105]
	v_mfma_f32_16x16x128_f8f6f4 v[94:97], v[134:141], v[26:33], v[166:169]
	v_mfma_f32_16x16x128_f8f6f4 v[86:89], v[142:149], v[26:33], v[170:173]
	v_mfma_f32_16x16x128_f8f6f4 v[78:81], v[134:141], v[34:41], v[174:177]
	v_mfma_f32_16x16x128_f8f6f4 v[74:77], v[142:149], v[34:41], v[178:181]
	v_mfma_f32_16x16x128_f8f6f4 v[70:73], v[134:141], v[42:49], v[182:185]
	v_mfma_f32_16x16x128_f8f6f4 v[66:69], v[142:149], v[42:49], v[186:189]
	s_setprio 0
	s_barrier
	s_mov_b32 m0, s63
	s_or_b32 s92, s91, 0x80
	ds_read_b128 v[150:153], v227 offset:49152
	ds_read_b128 v[154:157], v227 offset:50176
	ds_read_b128 v[158:161], v227 offset:51200
	ds_read_b128 v[162:165], v227 offset:52224
	ds_read_b128 v[166:169], v227 offset:53248
	ds_read_b128 v[170:173], v227 offset:54272
	ds_read_b128 v[174:177], v227 offset:55296
	ds_read_b128 v[178:181], v227 offset:56320
	buffer_load_dwordx4 v224, s[16:19], s92 offen lds
	s_add_i32 s92, s91, 0xac080
	s_mov_b32 m0, s64
	s_add_i32 s56, s56, 0xac080
	buffer_load_dwordx4 v224, s[16:19], s92 offen lds
	s_add_i32 s92, s91, 0x158080
	s_mov_b32 m0, s67
	s_add_i32 s91, s91, 0x204080
	buffer_load_dwordx4 v224, s[16:19], s92 offen lds
	s_mov_b32 m0, s68
	s_nop 0
	buffer_load_dwordx4 v224, s[16:19], s91 offen lds
	s_mov_b32 m0, s65
	s_nop 0
	buffer_load_dwordx4 v223, s[12:15], s57 offen lds
	s_mov_b32 m0, s66
	s_nop 0
	buffer_load_dwordx4 v223, s[12:15], s56 offen lds
	s_waitcnt vmcnt(8)
	s_waitcnt lgkmcnt(0)
	s_setprio 1
	s_barrier
	v_mfma_f32_16x16x128_f8f6f4 v[62:65], v[2:9], v[150:157], v[62:65]
	v_mfma_f32_16x16x128_f8f6f4 v[58:61], v[10:17], v[150:157], v[58:61]
	v_mfma_f32_16x16x128_f8f6f4 v[54:57], v[2:9], v[158:165], v[54:57]
	v_mfma_f32_16x16x128_f8f6f4 v[50:53], v[10:17], v[158:165], v[50:53]
	v_mfma_f32_16x16x128_f8f6f4 v[42:45], v[2:9], v[166:173], v[190:193]
	v_mfma_f32_16x16x128_f8f6f4 v[34:37], v[10:17], v[166:173], v[194:197]
	v_mfma_f32_16x16x128_f8f6f4 v[26:29], v[2:9], v[174:181], v[206:209]
	v_mfma_f32_16x16x128_f8f6f4 v[18:21], v[10:17], v[174:181], v[210:213]
	v_mfma_f32_16x16x128_f8f6f4 v[46:49], v[134:141], v[150:157], v[214:217]
	v_mfma_f32_16x16x128_f8f6f4 v[38:41], v[142:149], v[150:157], v[218:221]
	v_mfma_f32_16x16x128_f8f6f4 v[30:33], v[134:141], v[158:165], v[234:237]
	v_mfma_f32_16x16x128_f8f6f4 v[22:25], v[142:149], v[158:165], v[238:241]
	v_mfma_f32_16x16x128_f8f6f4 v[14:17], v[134:141], v[166:173], v[242:245]
	v_mfma_f32_16x16x128_f8f6f4 v[10:13], v[142:149], v[166:173], v[246:249]
	v_mfma_f32_16x16x128_f8f6f4 v[6:9], v[134:141], v[174:181], v[250:253]
	v_mfma_f32_16x16x128_f8f6f4 v[2:5], v[142:149], v[174:181], v[130:133]
	s_setprio 0
	s_barrier
	s_add_i32 s55, s55, 2
	s_addk_i32 s8, 0x100
	s_addk_i32 s9, 0x100
	s_cmp_ge_i32 s55, s3
	s_cbranch_scc0 .LBB0_1567
	v_pk_mul_f32 v[208:209], v[128:129], s[50:51] op_sel_hi:[1,0]
	v_pk_mul_f32 v[210:211], v[126:127], s[50:51] op_sel_hi:[1,0]
	v_pk_mul_f32 v[212:213], v[124:125], s[50:51] op_sel_hi:[1,0]
	v_pk_mul_f32 v[122:123], v[122:123], s[50:51] op_sel_hi:[1,0]
	v_pk_mul_f32 v[220:221], v[112:113], s[50:51] op_sel_hi:[1,0]
	v_pk_mul_f32 v[218:219], v[110:111], s[50:51] op_sel_hi:[1,0]
	v_pk_mul_f32 v[216:217], v[104:105], s[50:51] op_sel_hi:[1,0]
	v_pk_mul_f32 v[214:215], v[102:103], s[50:51] op_sel_hi:[1,0]
	v_pk_mul_f32 v[206:207], v[120:121], s[50:51] op_sel_hi:[1,0]
	v_pk_mul_f32 v[146:147], v[118:119], s[50:51] op_sel_hi:[1,0]
	v_pk_mul_f32 v[204:205], v[116:117], s[50:51] op_sel_hi:[1,0]
	v_pk_mul_f32 v[144:145], v[114:115], s[50:51] op_sel_hi:[1,0]
	v_pk_mul_f32 v[148:149], v[96:97], s[50:51] op_sel_hi:[1,0]
	v_pk_mul_f32 v[154:155], v[94:95], s[50:51] op_sel_hi:[1,0]
	v_pk_mul_f32 v[202:203], v[88:89], s[50:51] op_sel_hi:[1,0]
	v_pk_mul_f32 v[200:201], v[86:87], s[50:51] op_sel_hi:[1,0]
	v_pk_mul_f32 v[198:199], v[108:109], s[50:51] op_sel_hi:[1,0]
	v_pk_mul_f32 v[152:153], v[106:107], s[50:51] op_sel_hi:[1,0]
	v_pk_mul_f32 v[196:197], v[100:101], s[50:51] op_sel_hi:[1,0]
	v_pk_mul_f32 v[150:151], v[98:99], s[50:51] op_sel_hi:[1,0]
	v_pk_mul_f32 v[156:157], v[80:81], s[50:51] op_sel_hi:[1,0]
	v_pk_mul_f32 v[162:163], v[78:79], s[50:51] op_sel_hi:[1,0]
	v_pk_mul_f32 v[194:195], v[76:77], s[50:51] op_sel_hi:[1,0]
	v_pk_mul_f32 v[192:193], v[74:75], s[50:51] op_sel_hi:[1,0]
	v_pk_mul_f32 v[190:191], v[92:93], s[50:51] op_sel_hi:[1,0]
	v_pk_mul_f32 v[160:161], v[90:91], s[50:51] op_sel_hi:[1,0]
	v_pk_mul_f32 v[188:189], v[84:85], s[50:51] op_sel_hi:[1,0]
	v_pk_mul_f32 v[158:159], v[82:83], s[50:51] op_sel_hi:[1,0]
	v_pk_mul_f32 v[164:165], v[72:73], s[50:51] op_sel_hi:[1,0]
	v_pk_mul_f32 v[170:171], v[70:71], s[50:51] op_sel_hi:[1,0]
	v_pk_mul_f32 v[186:187], v[68:69], s[50:51] op_sel_hi:[1,0]
	v_pk_mul_f32 v[184:185], v[66:67], s[50:51] op_sel_hi:[1,0]
	v_pk_mul_f32 v[182:183], v[64:65], s[50:51] op_sel_hi:[1,0]
	v_pk_mul_f32 v[168:169], v[62:63], s[50:51] op_sel_hi:[1,0]
	v_pk_mul_f32 v[180:181], v[60:61], s[50:51] op_sel_hi:[1,0]
	v_pk_mul_f32 v[166:167], v[58:59], s[50:51] op_sel_hi:[1,0]
	v_pk_mul_f32 v[172:173], v[48:49], s[50:51] op_sel_hi:[1,0]
	v_pk_mul_f32 v[178:179], v[46:47], s[50:51] op_sel_hi:[1,0]
	v_pk_mul_f32 v[176:177], v[40:41], s[50:51] op_sel_hi:[1,0]
	v_pk_mul_f32 v[174:175], v[38:39], s[50:51] op_sel_hi:[1,0]
	v_pk_mul_f32 v[142:143], v[56:57], s[50:51] op_sel_hi:[1,0]
	v_pk_mul_f32 v[140:141], v[54:55], s[50:51] op_sel_hi:[1,0]
	v_pk_mul_f32 v[138:139], v[52:53], s[50:51] op_sel_hi:[1,0]
	v_pk_mul_f32 v[134:135], v[50:51], s[50:51] op_sel_hi:[1,0]
	v_pk_mul_f32 v[136:137], v[32:33], s[50:51] op_sel_hi:[1,0]
	v_pk_mul_f32 v[128:129], v[30:31], s[50:51] op_sel_hi:[1,0]
	v_pk_mul_f32 v[126:127], v[24:25], s[50:51] op_sel_hi:[1,0]
	v_pk_mul_f32 v[124:125], v[22:23], s[50:51] op_sel_hi:[1,0]
	v_pk_mul_f32 v[102:103], v[44:45], s[50:51] op_sel_hi:[1,0]
	v_pk_mul_f32 v[100:101], v[42:43], s[50:51] op_sel_hi:[1,0]
	v_pk_mul_f32 v[98:99], v[36:37], s[50:51] op_sel_hi:[1,0]
	v_pk_mul_f32 v[94:95], v[34:35], s[50:51] op_sel_hi:[1,0]
	v_pk_mul_f32 v[96:97], v[16:17], s[50:51] op_sel_hi:[1,0]
	v_pk_mul_f32 v[92:93], v[14:15], s[50:51] op_sel_hi:[1,0]
	v_pk_mul_f32 v[90:91], v[12:13], s[50:51] op_sel_hi:[1,0]
	v_pk_mul_f32 v[88:89], v[10:11], s[50:51] op_sel_hi:[1,0]
	v_pk_mul_f32 v[86:87], v[28:29], s[50:51] op_sel_hi:[1,0]
	v_pk_mul_f32 v[84:85], v[26:27], s[50:51] op_sel_hi:[1,0]
	v_pk_mul_f32 v[82:83], v[20:21], s[50:51] op_sel_hi:[1,0]
	v_pk_mul_f32 v[78:79], v[18:19], s[50:51] op_sel_hi:[1,0]
	v_pk_mul_f32 v[80:81], v[8:9], s[50:51] op_sel_hi:[1,0]
	v_pk_mul_f32 v[76:77], v[6:7], s[50:51] op_sel_hi:[1,0]
	v_pk_mul_f32 v[74:75], v[4:5], s[50:51] op_sel_hi:[1,0]
	v_pk_mul_f32 v[72:73], v[2:3], s[50:51] op_sel_hi:[1,0]
	s_and_b64 vcc, exec, s[48:49]
	s_cbranch_vccz .LBB0_1570
